# P0 adaLN: silu(cond) LDS table filled with all 20 loads per thread in flight (was 20 serial load-wait-compute-write steps)
# baseline (speedup 1.0000x reference)
; __device__ __forceinline__ float sigmoidf_(float x) { return __builtin_amdgcn_rcpf(1.f + __expf(-x)); }
; __global__ void __launch_bounds__(NTHR, 2) fwd_kernel(Args a) {
;     ...
;         __syncthreads();
;         for (int i = tid; i < 5 * DM; i += NTHR) { const float c = i < 4 * DM ? a.in[I_C][i] : a.in[I_CCTX][i - 4 * DM]; sl[i] = c * sigmoidf_(c); }
;         __syncthreads();
.LBB0_97:
	s_or_b64 exec, exec, s[4:5]
	v_mov_b32_e32 v0, v189
	s_movk_i32 s0, 0x2800
	s_nop 0
	v_readfirstlane_b32 s12, v0
	v_cmp_gt_i32_e32 vcc, s0, v0
	s_barrier
	s_and_saveexec_b64 s[0:1], vcc
	v_readlane_b32 s16, v254, 1
	v_readlane_b32 s18, v254, 3
	v_readlane_b32 s19, v254, 4
	v_readlane_b32 s22, v254, 7
	v_readlane_b32 s23, v254, 8
	v_readlane_b32 s17, v254, 2
	v_readlane_b32 s20, v254, 5
	v_readlane_b32 s21, v254, 6
	v_readlane_b32 s24, v254, 9
	v_readlane_b32 s25, v254, 10
	v_readlane_b32 s26, v254, 11
	v_readlane_b32 s27, v254, 12
	v_readlane_b32 s28, v254, 13
	v_readlane_b32 s29, v254, 14
	v_readlane_b32 s30, v254, 15
	v_readlane_b32 s31, v254, 16
	s_cbranch_execz .LBB0_100
	v_mov_b32_e32 v2, s18
	v_mov_b32_e32 v3, s19
	v_ashrrev_i32_e32 v1, 31, v0
	s_movk_i32 s4, 0x8000
	v_lshl_add_u64 v[2:3], v[0:1], 2, v[2:3]
	v_lshl_add_u32 v1, v0, 2, 0
	s_mov_b64 s[2:3], 0
	s_movk_i32 s13, 0x2000
	v_mov_b32_e32 v5, 0
	s_mov_b32 s5, -1
	s_mov_b64 s[8:9], 0x800
	s_movk_i32 s14, 0x25ff
	v_mov_b32_e32 v4, v0
	v_lshlrev_b32_e32 v9, 2, v0
	global_load_dword v10, v9, s[18:19]
	global_load_dword v11, v9, s[18:19] offset:2048
	v_add_u32_e32 v9, 0x1000, v9
	global_load_dword v12, v9, s[18:19]
	global_load_dword v13, v9, s[18:19] offset:2048
	v_add_u32_e32 v9, 0x1000, v9
	global_load_dword v14, v9, s[18:19]
	global_load_dword v15, v9, s[18:19] offset:2048
	v_add_u32_e32 v9, 0x1000, v9
	global_load_dword v16, v9, s[18:19]
	global_load_dword v17, v9, s[18:19] offset:2048
	v_add_u32_e32 v9, 0x1000, v9
	global_load_dword v18, v9, s[18:19]
	global_load_dword v19, v9, s[18:19] offset:2048
	v_add_u32_e32 v9, 0x1000, v9
	global_load_dword v20, v9, s[18:19]
	global_load_dword v21, v9, s[18:19] offset:2048
	v_add_u32_e32 v9, 0x1000, v9
	global_load_dword v22, v9, s[18:19]
	global_load_dword v23, v9, s[18:19] offset:2048
	v_add_u32_e32 v9, 0x1000, v9
	global_load_dword v24, v9, s[18:19]
	global_load_dword v25, v9, s[18:19] offset:2048
	v_lshlrev_b32_e32 v9, 2, v0
	global_load_dword v26, v9, s[22:23]
	global_load_dword v27, v9, s[22:23] offset:2048
	v_add_u32_e32 v9, 0x1000, v9
	global_load_dword v28, v9, s[22:23]
	global_load_dword v29, v9, s[22:23] offset:2048
	s_waitcnt vmcnt(19)
	v_mul_f32_e32 v8, 0xbfb8aa3b, v10
	v_exp_f32_e32 v8, v8
	s_nop 0
	v_add_f32_e32 v4, 1.0, v8
	v_rcp_f32_e32 v8, v4
	s_nop 0
	v_mul_f32_e32 v6, v10, v8
	ds_write_b32 v1, v6
	s_waitcnt vmcnt(18)
	v_mul_f32_e32 v8, 0xbfb8aa3b, v11
	v_exp_f32_e32 v8, v8
	s_nop 0
	v_add_f32_e32 v4, 1.0, v8
	v_rcp_f32_e32 v8, v4
	s_nop 0
	v_mul_f32_e32 v6, v11, v8
	ds_write_b32 v1, v6 offset:2048
	s_waitcnt vmcnt(17)
	v_mul_f32_e32 v8, 0xbfb8aa3b, v12
	v_exp_f32_e32 v8, v8
	s_nop 0
	v_add_f32_e32 v4, 1.0, v8
	v_rcp_f32_e32 v8, v4
	s_nop 0
	v_mul_f32_e32 v6, v12, v8
	ds_write_b32 v1, v6 offset:4096
	s_waitcnt vmcnt(16)
	v_mul_f32_e32 v8, 0xbfb8aa3b, v13
	v_exp_f32_e32 v8, v8
	s_nop 0
	v_add_f32_e32 v4, 1.0, v8
	v_rcp_f32_e32 v8, v4
	s_nop 0
	v_mul_f32_e32 v6, v13, v8
	ds_write_b32 v1, v6 offset:6144
	s_waitcnt vmcnt(15)
	v_mul_f32_e32 v8, 0xbfb8aa3b, v14
	v_exp_f32_e32 v8, v8
	s_nop 0
	v_add_f32_e32 v4, 1.0, v8
	v_rcp_f32_e32 v8, v4
	s_nop 0
	v_mul_f32_e32 v6, v14, v8
	ds_write_b32 v1, v6 offset:8192
	s_waitcnt vmcnt(14)
	v_mul_f32_e32 v8, 0xbfb8aa3b, v15
	v_exp_f32_e32 v8, v8
	s_nop 0
	v_add_f32_e32 v4, 1.0, v8
	v_rcp_f32_e32 v8, v4
	s_nop 0
	v_mul_f32_e32 v6, v15, v8
	ds_write_b32 v1, v6 offset:10240
	s_waitcnt vmcnt(13)
	v_mul_f32_e32 v8, 0xbfb8aa3b, v16
	v_exp_f32_e32 v8, v8
	s_nop 0
	v_add_f32_e32 v4, 1.0, v8
	v_rcp_f32_e32 v8, v4
	s_nop 0
	v_mul_f32_e32 v6, v16, v8
	ds_write_b32 v1, v6 offset:12288
	s_waitcnt vmcnt(12)
	v_mul_f32_e32 v8, 0xbfb8aa3b, v17
	v_exp_f32_e32 v8, v8
	s_nop 0
	v_add_f32_e32 v4, 1.0, v8
	v_rcp_f32_e32 v8, v4
	s_nop 0
	v_mul_f32_e32 v6, v17, v8
	ds_write_b32 v1, v6 offset:14336
	s_waitcnt vmcnt(11)
	v_mul_f32_e32 v8, 0xbfb8aa3b, v18
	v_exp_f32_e32 v8, v8
	s_nop 0
	v_add_f32_e32 v4, 1.0, v8
	v_rcp_f32_e32 v8, v4
	s_nop 0
	v_mul_f32_e32 v6, v18, v8
	ds_write_b32 v1, v6 offset:16384
	s_waitcnt vmcnt(10)
	v_mul_f32_e32 v8, 0xbfb8aa3b, v19
	v_exp_f32_e32 v8, v8
	s_nop 0
	v_add_f32_e32 v4, 1.0, v8
	v_rcp_f32_e32 v8, v4
	s_nop 0
	v_mul_f32_e32 v6, v19, v8
	ds_write_b32 v1, v6 offset:18432
	s_waitcnt vmcnt(9)
	v_mul_f32_e32 v8, 0xbfb8aa3b, v20
	v_exp_f32_e32 v8, v8
	s_nop 0
	v_add_f32_e32 v4, 1.0, v8
	v_rcp_f32_e32 v8, v4
	s_nop 0
	v_mul_f32_e32 v6, v20, v8
	ds_write_b32 v1, v6 offset:20480
	s_waitcnt vmcnt(8)
	v_mul_f32_e32 v8, 0xbfb8aa3b, v21
	v_exp_f32_e32 v8, v8
	s_nop 0
	v_add_f32_e32 v4, 1.0, v8
	v_rcp_f32_e32 v8, v4
	s_nop 0
	v_mul_f32_e32 v6, v21, v8
	ds_write_b32 v1, v6 offset:22528
	s_waitcnt vmcnt(7)
	v_mul_f32_e32 v8, 0xbfb8aa3b, v22
	v_exp_f32_e32 v8, v8
	s_nop 0
	v_add_f32_e32 v4, 1.0, v8
	v_rcp_f32_e32 v8, v4
	s_nop 0
	v_mul_f32_e32 v6, v22, v8
	ds_write_b32 v1, v6 offset:24576
	s_waitcnt vmcnt(6)
	v_mul_f32_e32 v8, 0xbfb8aa3b, v23
	v_exp_f32_e32 v8, v8
	s_nop 0
	v_add_f32_e32 v4, 1.0, v8
	v_rcp_f32_e32 v8, v4
	s_nop 0
	v_mul_f32_e32 v6, v23, v8
	ds_write_b32 v1, v6 offset:26624
	s_waitcnt vmcnt(5)
	v_mul_f32_e32 v8, 0xbfb8aa3b, v24
	v_exp_f32_e32 v8, v8
	s_nop 0
	v_add_f32_e32 v4, 1.0, v8
	v_rcp_f32_e32 v8, v4
	s_nop 0
	v_mul_f32_e32 v6, v24, v8
	ds_write_b32 v1, v6 offset:28672
	s_waitcnt vmcnt(4)
	v_mul_f32_e32 v8, 0xbfb8aa3b, v25
	v_exp_f32_e32 v8, v8
	s_nop 0
	v_add_f32_e32 v4, 1.0, v8
	v_rcp_f32_e32 v8, v4
	s_nop 0
	v_mul_f32_e32 v6, v25, v8
	ds_write_b32 v1, v6 offset:30720
	s_waitcnt vmcnt(3)
	v_mul_f32_e32 v8, 0xbfb8aa3b, v26
	v_exp_f32_e32 v8, v8
	s_nop 0
	v_add_f32_e32 v4, 1.0, v8
	v_rcp_f32_e32 v8, v4
	s_nop 0
	v_mul_f32_e32 v6, v26, v8
	ds_write_b32 v1, v6 offset:32768
	s_waitcnt vmcnt(2)
	v_mul_f32_e32 v8, 0xbfb8aa3b, v27
	v_exp_f32_e32 v8, v8
	s_nop 0
	v_add_f32_e32 v4, 1.0, v8
	v_rcp_f32_e32 v8, v4
	s_nop 0
	v_mul_f32_e32 v6, v27, v8
	ds_write_b32 v1, v6 offset:34816
	s_waitcnt vmcnt(1)
	v_mul_f32_e32 v8, 0xbfb8aa3b, v28
	v_exp_f32_e32 v8, v8
	s_nop 0
	v_add_f32_e32 v4, 1.0, v8
	v_rcp_f32_e32 v8, v4
	s_nop 0
	v_mul_f32_e32 v6, v28, v8
	ds_write_b32 v1, v6 offset:36864
	s_waitcnt vmcnt(0)
	v_mul_f32_e32 v8, 0xbfb8aa3b, v29
	v_exp_f32_e32 v8, v8
	s_nop 0
	v_add_f32_e32 v4, 1.0, v8
	v_rcp_f32_e32 v8, v4
	s_nop 0
	v_mul_f32_e32 v6, v29, v8
	ds_write_b32 v1, v6 offset:38912
